# RES epilogue: 8-element partial sum of squares per group with packed f32 (v_pk_mul_f32 + 3 v_pk_fma_f32 + add = 5 VALU instead of 11 scalar mul/fmac/add); same f32 products, adds re-associated
# speedup vs baseline: 1.0091x; 1.0091x over previous
.LBB0_321:
	v_cmp_lt_i32_e32 vcc, v176, v171
	v_lshl_add_u32 v154, s21, 8, v131
	v_lshl_or_b32 v152, s19, 8, v160
	v_cndmask_b32_e32 v155, v170, v176, vcc
	v_cmp_lt_i32_e32 vcc, v177, v171
	v_lshlrev_b32_e32 v164, 2, v155
	v_ashrrev_i32_e32 v153, 31, v152
	v_cndmask_b32_e32 v155, v170, v177, vcc
	v_lshlrev_b32_e32 v162, 2, v155
	v_ashrrev_i32_e32 v155, 31, v154
	v_lshlrev_b64 v[156:157], 11, v[154:155]
	v_lshl_add_u64 v[156:157], s[78:79], 0, v[156:157]
	v_lshl_add_u64 v[156:157], v[152:153], 1, v[156:157]
	s_lshl_b32 vcc_lo, s19, 2
	s_ashr_i32 vcc_hi, vcc_lo, 31
	s_waitcnt vmcnt(15)
	v_lshlrev_b32_e32 v182, 16, v186
	v_and_b32_e32 v183, 0xffff0000, v186
	v_lshlrev_b32_e32 v178, 16, v187
	v_and_b32_e32 v179, 0xffff0000, v187
	v_lshlrev_b32_e32 v184, 16, v188
	v_and_b32_e32 v185, 0xffff0000, v188
	v_lshlrev_b32_e32 v180, 16, v189
	v_and_b32_e32 v181, 0xffff0000, v189
	v_pk_add_f32 v[128:129], v[128:129], v[178:179]
	v_pk_add_f32 v[126:127], v[126:127], v[182:183]
	v_pk_add_f32 v[178:179], v[124:125], v[180:181]
	v_pk_add_f32 v[180:181], v[122:123], v[184:185]
	v_cvt_pk_bf16_f32 v122, v126, v127
	v_cvt_pk_bf16_f32 v123, v128, v129
	v_cvt_pk_bf16_f32 v124, v180, v181
	v_cvt_pk_bf16_f32 v125, v178, v179
	global_store_dwordx4 v[156:157], v[122:125], off
	s_nop 1
	v_pk_mul_f32 v[122:123], v[126:127], v[126:127]
	v_pk_fma_f32 v[122:123], v[128:129], v[128:129], v[122:123]
	v_pk_fma_f32 v[122:123], v[180:181], v[180:181], v[122:123]
	v_pk_fma_f32 v[122:123], v[178:179], v[178:179], v[122:123]
	v_add_f32_e32 v165, v122, v123
	s_waitcnt vmcnt(15)
	v_lshlrev_b32_e32 v126, 16, v190
	v_and_b32_e32 v127, 0xffff0000, v190
	v_lshlrev_b32_e32 v122, 16, v191
	v_and_b32_e32 v123, 0xffff0000, v191
	v_lshlrev_b32_e32 v128, 16, v192
	v_and_b32_e32 v129, 0xffff0000, v192
	v_lshlrev_b32_e32 v124, 16, v193
	v_and_b32_e32 v125, 0xffff0000, v193
	v_pk_add_f32 v[120:121], v[120:121], v[122:123]
	v_pk_add_f32 v[118:119], v[118:119], v[126:127]
	v_pk_add_f32 v[122:123], v[116:117], v[124:125]
	v_pk_add_f32 v[124:125], v[114:115], v[128:129]
	v_cvt_pk_bf16_f32 v114, v118, v119
	v_cvt_pk_bf16_f32 v115, v120, v121
	v_cvt_pk_bf16_f32 v116, v124, v125
	v_cvt_pk_bf16_f32 v117, v122, v123
	global_store_dwordx4 v[156:157], v[114:117], off offset:256
	s_nop 1
	v_pk_mul_f32 v[114:115], v[118:119], v[118:119]
	v_pk_fma_f32 v[114:115], v[120:121], v[120:121], v[114:115]
	v_pk_fma_f32 v[114:115], v[124:125], v[124:125], v[114:115]
	v_pk_fma_f32 v[114:115], v[122:123], v[122:123], v[114:115]
	v_add_f32_e32 v114, v114, v115
	v_add_f32_e32 v114, v165, v114
	ds_bpermute_b32 v115, v164, v114
	s_waitcnt lgkmcnt(0)
	v_add_f32_e32 v114, v114, v115
	ds_bpermute_b32 v115, v162, v114
	s_and_saveexec_b64 s[12:13], s[6:7]
	s_cbranch_execz .LBB0_323
	s_waitcnt lgkmcnt(0)
	v_add_f32_e32 v116, v114, v115
	v_lshlrev_b64 v[114:115], 6, v[154:155]
	v_lshl_add_u64 v[114:115], s[82:83], 0, v[114:115]
	v_lshl_add_u64 v[114:115], vcc, 2, v[114:115]
	s_lshl_b32 s60, s53, 2
	v_lshl_add_u64 v[114:115], v[114:115], 0, s[60:61]
	global_store_dword v[114:115], v116, off
.LBB0_323:
	s_or_b64 exec, exec, s[12:13]
	v_or_b32_e32 v114, 16, v154
	s_waitcnt lgkmcnt(0)
	v_ashrrev_i32_e32 v115, 31, v114
	v_lshlrev_b64 v[116:117], 11, v[114:115]
	v_lshl_add_u64 v[116:117], s[78:79], 0, v[116:117]
	v_lshl_add_u64 v[120:121], v[152:153], 1, v[116:117]
	s_waitcnt vmcnt(16)
	v_lshlrev_b32_e32 v122, 16, v194
	v_and_b32_e32 v123, 0xffff0000, v194
	v_lshlrev_b32_e32 v116, 16, v195
	v_and_b32_e32 v117, 0xffff0000, v195
	v_lshlrev_b32_e32 v124, 16, v196
	v_and_b32_e32 v125, 0xffff0000, v196
	v_lshlrev_b32_e32 v118, 16, v197
	v_and_b32_e32 v119, 0xffff0000, v197
	v_pk_add_f32 v[112:113], v[112:113], v[116:117]
	v_pk_add_f32 v[110:111], v[110:111], v[122:123]
	v_pk_add_f32 v[116:117], v[108:109], v[118:119]
	v_pk_add_f32 v[118:119], v[106:107], v[124:125]
	v_cvt_pk_bf16_f32 v106, v110, v111
	v_cvt_pk_bf16_f32 v107, v112, v113
	v_cvt_pk_bf16_f32 v108, v118, v119
	v_cvt_pk_bf16_f32 v109, v116, v117
	global_store_dwordx4 v[120:121], v[106:109], off
	s_nop 1
	v_pk_mul_f32 v[106:107], v[110:111], v[110:111]
	v_pk_fma_f32 v[106:107], v[112:113], v[112:113], v[106:107]
	v_pk_fma_f32 v[106:107], v[118:119], v[118:119], v[106:107]
	v_pk_fma_f32 v[106:107], v[116:117], v[116:117], v[106:107]
	v_add_f32_e32 v116, v106, v107
	s_waitcnt vmcnt(16)
	v_lshlrev_b32_e32 v110, 16, v198
	v_and_b32_e32 v111, 0xffff0000, v198
	v_lshlrev_b32_e32 v106, 16, v199
	v_and_b32_e32 v107, 0xffff0000, v199
	v_lshlrev_b32_e32 v112, 16, v200
	v_and_b32_e32 v113, 0xffff0000, v200
	v_lshlrev_b32_e32 v108, 16, v201
	v_and_b32_e32 v109, 0xffff0000, v201
	v_pk_add_f32 v[104:105], v[104:105], v[106:107]
	v_pk_add_f32 v[102:103], v[102:103], v[110:111]
	v_pk_add_f32 v[106:107], v[100:101], v[108:109]
	v_pk_add_f32 v[108:109], v[98:99], v[112:113]
	v_cvt_pk_bf16_f32 v98, v102, v103
	v_cvt_pk_bf16_f32 v99, v104, v105
	v_cvt_pk_bf16_f32 v100, v108, v109
	v_cvt_pk_bf16_f32 v101, v106, v107
	global_store_dwordx4 v[120:121], v[98:101], off offset:256
	s_nop 1
	v_pk_mul_f32 v[98:99], v[102:103], v[102:103]
	v_pk_fma_f32 v[98:99], v[104:105], v[104:105], v[98:99]
	v_pk_fma_f32 v[98:99], v[108:109], v[108:109], v[98:99]
	v_pk_fma_f32 v[98:99], v[106:107], v[106:107], v[98:99]
	v_add_f32_e32 v98, v98, v99
	v_add_f32_e32 v98, v116, v98
	ds_bpermute_b32 v99, v164, v98
	s_waitcnt lgkmcnt(0)
	v_add_f32_e32 v98, v98, v99
	ds_bpermute_b32 v99, v162, v98
	s_and_saveexec_b64 s[12:13], s[6:7]
	s_cbranch_execz .LBB0_325
	s_waitcnt lgkmcnt(0)
	v_add_f32_e32 v100, v98, v99
	v_lshlrev_b64 v[98:99], 6, v[114:115]
	v_lshl_add_u64 v[98:99], s[82:83], 0, v[98:99]
	v_lshl_add_u64 v[98:99], vcc, 2, v[98:99]
	s_lshl_b32 s60, s53, 2
	v_lshl_add_u64 v[98:99], v[98:99], 0, s[60:61]
	global_store_dword v[98:99], v100, off
.LBB0_325:
	s_or_b64 exec, exec, s[12:13]
	v_or_b32_e32 v98, 32, v154
	s_waitcnt lgkmcnt(0)
	v_ashrrev_i32_e32 v99, 31, v98
	v_lshlrev_b64 v[100:101], 11, v[98:99]
	v_lshl_add_u64 v[100:101], s[78:79], 0, v[100:101]
	v_lshl_add_u64 v[104:105], v[152:153], 1, v[100:101]
	s_waitcnt vmcnt(17)
	v_lshlrev_b32_e32 v106, 16, v202
	v_and_b32_e32 v107, 0xffff0000, v202
	v_lshlrev_b32_e32 v100, 16, v203
	v_and_b32_e32 v101, 0xffff0000, v203
	v_lshlrev_b32_e32 v108, 16, v204
	v_and_b32_e32 v109, 0xffff0000, v204
	v_lshlrev_b32_e32 v102, 16, v205
	v_and_b32_e32 v103, 0xffff0000, v205
	v_pk_add_f32 v[96:97], v[96:97], v[100:101]
	v_pk_add_f32 v[94:95], v[94:95], v[106:107]
	v_pk_add_f32 v[100:101], v[92:93], v[102:103]
	v_pk_add_f32 v[102:103], v[90:91], v[108:109]
	v_cvt_pk_bf16_f32 v90, v94, v95
	v_cvt_pk_bf16_f32 v91, v96, v97
	v_cvt_pk_bf16_f32 v92, v102, v103
	v_cvt_pk_bf16_f32 v93, v100, v101
	global_store_dwordx4 v[104:105], v[90:93], off
	s_nop 1
	v_pk_mul_f32 v[90:91], v[94:95], v[94:95]
	v_pk_fma_f32 v[90:91], v[96:97], v[96:97], v[90:91]
	v_pk_fma_f32 v[90:91], v[102:103], v[102:103], v[90:91]
	v_pk_fma_f32 v[90:91], v[100:101], v[100:101], v[90:91]
	v_add_f32_e32 v100, v90, v91
	s_waitcnt vmcnt(17)
	v_lshlrev_b32_e32 v94, 16, v206
	v_and_b32_e32 v95, 0xffff0000, v206
	v_lshlrev_b32_e32 v90, 16, v207
	v_and_b32_e32 v91, 0xffff0000, v207
	v_lshlrev_b32_e32 v96, 16, v208
	v_and_b32_e32 v97, 0xffff0000, v208
	v_lshlrev_b32_e32 v92, 16, v209
	v_and_b32_e32 v93, 0xffff0000, v209
	v_pk_add_f32 v[88:89], v[88:89], v[90:91]
	v_pk_add_f32 v[86:87], v[86:87], v[94:95]
	v_pk_add_f32 v[90:91], v[84:85], v[92:93]
	v_pk_add_f32 v[92:93], v[82:83], v[96:97]
	v_cvt_pk_bf16_f32 v82, v86, v87
	v_cvt_pk_bf16_f32 v83, v88, v89
	v_cvt_pk_bf16_f32 v84, v92, v93
	v_cvt_pk_bf16_f32 v85, v90, v91
	global_store_dwordx4 v[104:105], v[82:85], off offset:256
	s_nop 1
	v_pk_mul_f32 v[82:83], v[86:87], v[86:87]
	v_pk_fma_f32 v[82:83], v[88:89], v[88:89], v[82:83]
	v_pk_fma_f32 v[82:83], v[92:93], v[92:93], v[82:83]
	v_pk_fma_f32 v[82:83], v[90:91], v[90:91], v[82:83]
	v_add_f32_e32 v82, v82, v83
	v_add_f32_e32 v82, v100, v82
	ds_bpermute_b32 v83, v164, v82
	s_waitcnt lgkmcnt(0)
	v_add_f32_e32 v82, v82, v83
	ds_bpermute_b32 v83, v162, v82
	s_and_saveexec_b64 s[12:13], s[6:7]
	s_cbranch_execz .LBB0_327
	s_waitcnt lgkmcnt(0)
	v_add_f32_e32 v84, v82, v83
	v_lshlrev_b64 v[82:83], 6, v[98:99]
	v_lshl_add_u64 v[82:83], s[82:83], 0, v[82:83]
	v_lshl_add_u64 v[82:83], vcc, 2, v[82:83]
	s_lshl_b32 s60, s53, 2
	v_lshl_add_u64 v[82:83], v[82:83], 0, s[60:61]
	global_store_dword v[82:83], v84, off
.LBB0_327:
	s_or_b64 exec, exec, s[12:13]
	v_or_b32_e32 v82, 48, v154
	s_waitcnt lgkmcnt(0)
	v_ashrrev_i32_e32 v83, 31, v82
	v_lshlrev_b64 v[84:85], 11, v[82:83]
	v_lshl_add_u64 v[84:85], s[78:79], 0, v[84:85]
	v_lshl_add_u64 v[88:89], v[152:153], 1, v[84:85]
	s_waitcnt vmcnt(18)
	v_lshlrev_b32_e32 v90, 16, v210
	v_and_b32_e32 v91, 0xffff0000, v210
	v_lshlrev_b32_e32 v84, 16, v211
	v_and_b32_e32 v85, 0xffff0000, v211
	v_lshlrev_b32_e32 v92, 16, v212
	v_and_b32_e32 v93, 0xffff0000, v212
	v_lshlrev_b32_e32 v86, 16, v213
	v_and_b32_e32 v87, 0xffff0000, v213
	v_pk_add_f32 v[80:81], v[80:81], v[84:85]
	v_pk_add_f32 v[78:79], v[78:79], v[90:91]
	v_pk_add_f32 v[84:85], v[76:77], v[86:87]
	v_pk_add_f32 v[86:87], v[74:75], v[92:93]
	v_cvt_pk_bf16_f32 v74, v78, v79
	v_cvt_pk_bf16_f32 v75, v80, v81
	v_cvt_pk_bf16_f32 v76, v86, v87
	v_cvt_pk_bf16_f32 v77, v84, v85
	global_store_dwordx4 v[88:89], v[74:77], off
	s_nop 1
	v_pk_mul_f32 v[74:75], v[78:79], v[78:79]
	v_pk_fma_f32 v[74:75], v[80:81], v[80:81], v[74:75]
	v_pk_fma_f32 v[74:75], v[86:87], v[86:87], v[74:75]
	v_pk_fma_f32 v[74:75], v[84:85], v[84:85], v[74:75]
	v_add_f32_e32 v84, v74, v75
	s_waitcnt vmcnt(18)
	v_lshlrev_b32_e32 v78, 16, v214
	v_and_b32_e32 v79, 0xffff0000, v214
	v_lshlrev_b32_e32 v74, 16, v215
	v_and_b32_e32 v75, 0xffff0000, v215
	v_lshlrev_b32_e32 v80, 16, v216
	v_and_b32_e32 v81, 0xffff0000, v216
	v_lshlrev_b32_e32 v76, 16, v217
	v_and_b32_e32 v77, 0xffff0000, v217
	v_pk_add_f32 v[72:73], v[72:73], v[74:75]
	v_pk_add_f32 v[70:71], v[70:71], v[78:79]
	v_pk_add_f32 v[74:75], v[68:69], v[76:77]
	v_pk_add_f32 v[76:77], v[66:67], v[80:81]
	v_cvt_pk_bf16_f32 v66, v70, v71
	v_cvt_pk_bf16_f32 v67, v72, v73
	v_cvt_pk_bf16_f32 v68, v76, v77
	v_cvt_pk_bf16_f32 v69, v74, v75
	global_store_dwordx4 v[88:89], v[66:69], off offset:256
	s_nop 1
	v_pk_mul_f32 v[66:67], v[70:71], v[70:71]
	v_pk_fma_f32 v[66:67], v[72:73], v[72:73], v[66:67]
	v_pk_fma_f32 v[66:67], v[76:77], v[76:77], v[66:67]
	v_pk_fma_f32 v[66:67], v[74:75], v[74:75], v[66:67]
	v_add_f32_e32 v66, v66, v67
	v_add_f32_e32 v66, v84, v66
	ds_bpermute_b32 v67, v164, v66
	s_waitcnt lgkmcnt(0)
	v_add_f32_e32 v66, v66, v67
	ds_bpermute_b32 v67, v162, v66
	s_and_saveexec_b64 s[12:13], s[6:7]
	s_cbranch_execz .LBB0_329
	s_waitcnt lgkmcnt(0)
	v_add_f32_e32 v68, v66, v67
	v_lshlrev_b64 v[66:67], 6, v[82:83]
	v_lshl_add_u64 v[66:67], s[82:83], 0, v[66:67]
	v_lshl_add_u64 v[66:67], vcc, 2, v[66:67]
	s_lshl_b32 s60, s53, 2
	v_lshl_add_u64 v[66:67], v[66:67], 0, s[60:61]
	global_store_dword v[66:67], v68, off
.LBB0_329:
	s_or_b64 exec, exec, s[12:13]
	v_add_u32_e32 v66, 0x80, v154
	s_waitcnt lgkmcnt(0)
	v_ashrrev_i32_e32 v67, 31, v66
	v_lshlrev_b64 v[68:69], 11, v[66:67]
	v_lshl_add_u64 v[68:69], s[78:79], 0, v[68:69]
	v_lshl_add_u64 v[72:73], v[152:153], 1, v[68:69]
	s_waitcnt vmcnt(19)
	v_lshlrev_b32_e32 v74, 16, v218
	v_and_b32_e32 v75, 0xffff0000, v218
	v_lshlrev_b32_e32 v68, 16, v219
	v_and_b32_e32 v69, 0xffff0000, v219
	v_lshlrev_b32_e32 v76, 16, v220
	v_and_b32_e32 v77, 0xffff0000, v220
	v_lshlrev_b32_e32 v70, 16, v221
	v_and_b32_e32 v71, 0xffff0000, v221
	v_pk_add_f32 v[64:65], v[64:65], v[68:69]
	v_pk_add_f32 v[62:63], v[62:63], v[74:75]
	v_pk_add_f32 v[68:69], v[60:61], v[70:71]
	v_pk_add_f32 v[70:71], v[58:59], v[76:77]
	v_cvt_pk_bf16_f32 v58, v62, v63
	v_cvt_pk_bf16_f32 v59, v64, v65
	v_cvt_pk_bf16_f32 v60, v70, v71
	v_cvt_pk_bf16_f32 v61, v68, v69
	global_store_dwordx4 v[72:73], v[58:61], off
	s_nop 1
	v_pk_mul_f32 v[58:59], v[62:63], v[62:63]
	v_pk_fma_f32 v[58:59], v[64:65], v[64:65], v[58:59]
	v_pk_fma_f32 v[58:59], v[70:71], v[70:71], v[58:59]
	v_pk_fma_f32 v[58:59], v[68:69], v[68:69], v[58:59]
	v_add_f32_e32 v68, v58, v59
	s_waitcnt vmcnt(19)
	v_lshlrev_b32_e32 v62, 16, v222
	v_and_b32_e32 v63, 0xffff0000, v222
	v_lshlrev_b32_e32 v58, 16, v223
	v_and_b32_e32 v59, 0xffff0000, v223
	v_lshlrev_b32_e32 v64, 16, v224
	v_and_b32_e32 v65, 0xffff0000, v224
	v_lshlrev_b32_e32 v60, 16, v225
	v_and_b32_e32 v61, 0xffff0000, v225
	v_pk_add_f32 v[56:57], v[56:57], v[58:59]
	v_pk_add_f32 v[54:55], v[54:55], v[62:63]
	v_pk_add_f32 v[58:59], v[52:53], v[60:61]
	v_pk_add_f32 v[60:61], v[50:51], v[64:65]
	v_cvt_pk_bf16_f32 v50, v54, v55
	v_cvt_pk_bf16_f32 v51, v56, v57
	v_cvt_pk_bf16_f32 v52, v60, v61
	v_cvt_pk_bf16_f32 v53, v58, v59
	global_store_dwordx4 v[72:73], v[50:53], off offset:256
	s_nop 1
	v_pk_mul_f32 v[50:51], v[54:55], v[54:55]
	v_pk_fma_f32 v[50:51], v[56:57], v[56:57], v[50:51]
	v_pk_fma_f32 v[50:51], v[60:61], v[60:61], v[50:51]
	v_pk_fma_f32 v[50:51], v[58:59], v[58:59], v[50:51]
	v_add_f32_e32 v50, v50, v51
	v_add_f32_e32 v50, v68, v50
	ds_bpermute_b32 v51, v164, v50
	s_waitcnt lgkmcnt(0)
	v_add_f32_e32 v50, v50, v51
	ds_bpermute_b32 v51, v162, v50
	s_and_saveexec_b64 s[12:13], s[6:7]
	s_cbranch_execz .LBB0_331
	s_waitcnt lgkmcnt(0)
	v_add_f32_e32 v52, v50, v51
	v_lshlrev_b64 v[50:51], 6, v[66:67]
	v_lshl_add_u64 v[50:51], s[82:83], 0, v[50:51]
	v_lshl_add_u64 v[50:51], vcc, 2, v[50:51]
	s_lshl_b32 s60, s53, 2
	v_lshl_add_u64 v[50:51], v[50:51], 0, s[60:61]
	global_store_dword v[50:51], v52, off
.LBB0_331:
	s_or_b64 exec, exec, s[12:13]
	v_add_u32_e32 v50, 0x90, v154
	s_waitcnt lgkmcnt(0)
	v_ashrrev_i32_e32 v51, 31, v50
	v_lshlrev_b64 v[52:53], 11, v[50:51]
	v_lshl_add_u64 v[52:53], s[78:79], 0, v[52:53]
	v_lshl_add_u64 v[56:57], v[152:153], 1, v[52:53]
	s_waitcnt vmcnt(20)
	v_lshlrev_b32_e32 v58, 16, v226
	v_and_b32_e32 v59, 0xffff0000, v226
	v_lshlrev_b32_e32 v52, 16, v227
	v_and_b32_e32 v53, 0xffff0000, v227
	v_lshlrev_b32_e32 v60, 16, v228
	v_and_b32_e32 v61, 0xffff0000, v228
	v_lshlrev_b32_e32 v54, 16, v229
	v_and_b32_e32 v55, 0xffff0000, v229
	v_pk_add_f32 v[48:49], v[48:49], v[52:53]
	v_pk_add_f32 v[46:47], v[46:47], v[58:59]
	v_pk_add_f32 v[52:53], v[44:45], v[54:55]
	v_pk_add_f32 v[54:55], v[42:43], v[60:61]
	v_cvt_pk_bf16_f32 v42, v46, v47
	v_cvt_pk_bf16_f32 v43, v48, v49
	v_cvt_pk_bf16_f32 v44, v54, v55
	v_cvt_pk_bf16_f32 v45, v52, v53
	global_store_dwordx4 v[56:57], v[42:45], off
	s_nop 1
	v_pk_mul_f32 v[42:43], v[46:47], v[46:47]
	v_pk_fma_f32 v[42:43], v[48:49], v[48:49], v[42:43]
	v_pk_fma_f32 v[42:43], v[54:55], v[54:55], v[42:43]
	v_pk_fma_f32 v[42:43], v[52:53], v[52:53], v[42:43]
	v_add_f32_e32 v52, v42, v43
	s_waitcnt vmcnt(20)
	v_lshlrev_b32_e32 v46, 16, v230
	v_and_b32_e32 v47, 0xffff0000, v230
	v_lshlrev_b32_e32 v42, 16, v231
	v_and_b32_e32 v43, 0xffff0000, v231
	v_lshlrev_b32_e32 v48, 16, v232
	v_and_b32_e32 v49, 0xffff0000, v232
	v_lshlrev_b32_e32 v44, 16, v233
	v_and_b32_e32 v45, 0xffff0000, v233
	v_pk_add_f32 v[40:41], v[40:41], v[42:43]
	v_pk_add_f32 v[38:39], v[38:39], v[46:47]
	v_pk_add_f32 v[42:43], v[36:37], v[44:45]
	v_pk_add_f32 v[44:45], v[34:35], v[48:49]
	v_cvt_pk_bf16_f32 v34, v38, v39
	v_cvt_pk_bf16_f32 v35, v40, v41
	v_cvt_pk_bf16_f32 v36, v44, v45
	v_cvt_pk_bf16_f32 v37, v42, v43
	global_store_dwordx4 v[56:57], v[34:37], off offset:256
	s_nop 1
	v_pk_mul_f32 v[34:35], v[38:39], v[38:39]
	v_pk_fma_f32 v[34:35], v[40:41], v[40:41], v[34:35]
	v_pk_fma_f32 v[34:35], v[44:45], v[44:45], v[34:35]
	v_pk_fma_f32 v[34:35], v[42:43], v[42:43], v[34:35]
	v_add_f32_e32 v34, v34, v35
	v_add_f32_e32 v34, v52, v34
	ds_bpermute_b32 v35, v164, v34
	s_waitcnt lgkmcnt(0)
	v_add_f32_e32 v34, v34, v35
	ds_bpermute_b32 v35, v162, v34
	s_and_saveexec_b64 s[12:13], s[6:7]
	s_cbranch_execz .LBB0_333
	s_waitcnt lgkmcnt(0)
	v_add_f32_e32 v36, v34, v35
	v_lshlrev_b64 v[34:35], 6, v[50:51]
	v_lshl_add_u64 v[34:35], s[82:83], 0, v[34:35]
	v_lshl_add_u64 v[34:35], vcc, 2, v[34:35]
	s_lshl_b32 s60, s53, 2
	v_lshl_add_u64 v[34:35], v[34:35], 0, s[60:61]
	global_store_dword v[34:35], v36, off
.LBB0_333:
	s_or_b64 exec, exec, s[12:13]
	v_add_u32_e32 v34, 0xa0, v154
	s_waitcnt lgkmcnt(0)
	v_ashrrev_i32_e32 v35, 31, v34
	v_lshlrev_b64 v[36:37], 11, v[34:35]
	v_lshl_add_u64 v[36:37], s[78:79], 0, v[36:37]
	v_lshl_add_u64 v[40:41], v[152:153], 1, v[36:37]
	s_waitcnt vmcnt(21)
	v_lshlrev_b32_e32 v42, 16, v234
	v_and_b32_e32 v43, 0xffff0000, v234
	v_lshlrev_b32_e32 v36, 16, v235
	v_and_b32_e32 v37, 0xffff0000, v235
	v_lshlrev_b32_e32 v44, 16, v236
	v_and_b32_e32 v45, 0xffff0000, v236
	v_lshlrev_b32_e32 v38, 16, v237
	v_and_b32_e32 v39, 0xffff0000, v237
	v_pk_add_f32 v[32:33], v[32:33], v[36:37]
	v_pk_add_f32 v[30:31], v[30:31], v[42:43]
	v_pk_add_f32 v[36:37], v[28:29], v[38:39]
	v_pk_add_f32 v[38:39], v[26:27], v[44:45]
	v_cvt_pk_bf16_f32 v26, v30, v31
	v_cvt_pk_bf16_f32 v27, v32, v33
	v_cvt_pk_bf16_f32 v28, v38, v39
	v_cvt_pk_bf16_f32 v29, v36, v37
	global_store_dwordx4 v[40:41], v[26:29], off
	s_nop 1
	v_pk_mul_f32 v[26:27], v[30:31], v[30:31]
	v_pk_fma_f32 v[26:27], v[32:33], v[32:33], v[26:27]
	v_pk_fma_f32 v[26:27], v[38:39], v[38:39], v[26:27]
	v_pk_fma_f32 v[26:27], v[36:37], v[36:37], v[26:27]
	v_add_f32_e32 v36, v26, v27
	s_waitcnt vmcnt(21)
	v_lshlrev_b32_e32 v30, 16, v238
	v_and_b32_e32 v31, 0xffff0000, v238
	v_lshlrev_b32_e32 v26, 16, v239
	v_and_b32_e32 v27, 0xffff0000, v239
	v_lshlrev_b32_e32 v32, 16, v240
	v_and_b32_e32 v33, 0xffff0000, v240
	v_lshlrev_b32_e32 v28, 16, v241
	v_and_b32_e32 v29, 0xffff0000, v241
	v_pk_add_f32 v[24:25], v[24:25], v[26:27]
	v_pk_add_f32 v[22:23], v[22:23], v[30:31]
	v_pk_add_f32 v[26:27], v[20:21], v[28:29]
	v_pk_add_f32 v[28:29], v[18:19], v[32:33]
	v_cvt_pk_bf16_f32 v18, v22, v23
	v_cvt_pk_bf16_f32 v19, v24, v25
	v_cvt_pk_bf16_f32 v20, v28, v29
	v_cvt_pk_bf16_f32 v21, v26, v27
	global_store_dwordx4 v[40:41], v[18:21], off offset:256
	s_nop 1
	v_pk_mul_f32 v[18:19], v[22:23], v[22:23]
	v_pk_fma_f32 v[18:19], v[24:25], v[24:25], v[18:19]
	v_pk_fma_f32 v[18:19], v[28:29], v[28:29], v[18:19]
	v_pk_fma_f32 v[18:19], v[26:27], v[26:27], v[18:19]
	v_add_f32_e32 v18, v18, v19
	v_add_f32_e32 v18, v36, v18
	ds_bpermute_b32 v19, v164, v18
	s_waitcnt lgkmcnt(0)
	v_add_f32_e32 v18, v18, v19
	ds_bpermute_b32 v19, v162, v18
	s_and_saveexec_b64 s[12:13], s[6:7]
	s_cbranch_execz .LBB0_335
	s_waitcnt lgkmcnt(0)
	v_add_f32_e32 v20, v18, v19
	v_lshlrev_b64 v[18:19], 6, v[34:35]
	v_lshl_add_u64 v[18:19], s[82:83], 0, v[18:19]
	v_lshl_add_u64 v[18:19], vcc, 2, v[18:19]
	s_lshl_b32 s60, s53, 2
	v_lshl_add_u64 v[18:19], v[18:19], 0, s[60:61]
	global_store_dword v[18:19], v20, off
.LBB0_335:
	s_or_b64 exec, exec, s[12:13]
	v_add_u32_e32 v18, 0xb0, v154
	s_waitcnt lgkmcnt(0)
	v_ashrrev_i32_e32 v19, 31, v18
	v_lshlrev_b64 v[20:21], 11, v[18:19]
	v_lshl_add_u64 v[20:21], s[78:79], 0, v[20:21]
	v_lshl_add_u64 v[24:25], v[152:153], 1, v[20:21]
	s_waitcnt vmcnt(22)
	v_lshlrev_b32_e32 v26, 16, v242
	v_and_b32_e32 v27, 0xffff0000, v242
	v_lshlrev_b32_e32 v20, 16, v243
	v_and_b32_e32 v21, 0xffff0000, v243
	v_lshlrev_b32_e32 v28, 16, v244
	v_and_b32_e32 v29, 0xffff0000, v244
	v_lshlrev_b32_e32 v22, 16, v245
	v_and_b32_e32 v23, 0xffff0000, v245
	v_pk_add_f32 v[16:17], v[16:17], v[20:21]
	v_pk_add_f32 v[14:15], v[14:15], v[26:27]
	v_pk_add_f32 v[20:21], v[12:13], v[22:23]
	v_pk_add_f32 v[22:23], v[10:11], v[28:29]
	v_cvt_pk_bf16_f32 v10, v14, v15
	v_cvt_pk_bf16_f32 v11, v16, v17
	v_cvt_pk_bf16_f32 v12, v22, v23
	v_cvt_pk_bf16_f32 v13, v20, v21
	global_store_dwordx4 v[24:25], v[10:13], off
	s_nop 1
	v_pk_mul_f32 v[10:11], v[14:15], v[14:15]
	v_pk_fma_f32 v[10:11], v[16:17], v[16:17], v[10:11]
	v_pk_fma_f32 v[10:11], v[22:23], v[22:23], v[10:11]
	v_pk_fma_f32 v[10:11], v[20:21], v[20:21], v[10:11]
	v_add_f32_e32 v20, v10, v11
	s_waitcnt vmcnt(22)
	v_lshlrev_b32_e32 v14, 16, v246
	v_and_b32_e32 v15, 0xffff0000, v246
	v_lshlrev_b32_e32 v10, 16, v247
	v_and_b32_e32 v11, 0xffff0000, v247
	v_lshlrev_b32_e32 v16, 16, v248
	v_and_b32_e32 v17, 0xffff0000, v248
	v_lshlrev_b32_e32 v12, 16, v249
	v_and_b32_e32 v13, 0xffff0000, v249
	v_pk_add_f32 v[8:9], v[8:9], v[10:11]
	v_pk_add_f32 v[6:7], v[6:7], v[14:15]
	v_pk_add_f32 v[10:11], v[4:5], v[12:13]
	v_pk_add_f32 v[12:13], v[2:3], v[16:17]
	v_cvt_pk_bf16_f32 v2, v6, v7
	v_cvt_pk_bf16_f32 v3, v8, v9
	v_cvt_pk_bf16_f32 v4, v12, v13
	v_cvt_pk_bf16_f32 v5, v10, v11
	global_store_dwordx4 v[24:25], v[2:5], off offset:256
	s_nop 1
	v_pk_mul_f32 v[2:3], v[6:7], v[6:7]
	v_pk_fma_f32 v[2:3], v[8:9], v[8:9], v[2:3]
	v_pk_fma_f32 v[2:3], v[12:13], v[12:13], v[2:3]
	v_pk_fma_f32 v[2:3], v[10:11], v[10:11], v[2:3]
	v_add_f32_e32 v2, v2, v3
	v_add_f32_e32 v2, v20, v2
	ds_bpermute_b32 v3, v164, v2
	s_waitcnt lgkmcnt(0)
	v_add_f32_e32 v2, v2, v3
	ds_bpermute_b32 v3, v162, v2
	s_and_saveexec_b64 s[12:13], s[6:7]
	s_cbranch_execz .LBB0_337
	s_waitcnt lgkmcnt(0)
	v_add_f32_e32 v4, v2, v3
	v_lshlrev_b64 v[2:3], 6, v[18:19]
	v_lshl_add_u64 v[2:3], s[82:83], 0, v[2:3]
	v_lshl_add_u64 v[2:3], vcc, 2, v[2:3]
	s_lshl_b32 s60, s53, 2
	v_lshl_add_u64 v[2:3], v[2:3], 0, s[60:61]
	global_store_dword v[2:3], v4, off
